# attention loop: K/V global loads issued early in the QK phase into the consumed-P registers, K ring 2 pairs deep, one wait per K pair / per two V fragments
# baseline (speedup 1.0000x reference)
; __device__ __forceinline__ void finishSM(f32x16& p0, f32x16& p1, float alpha, float& l_reg, bf16x8& pa0, bf16x8& pa1, bf16x8& pa2, bf16x8& pa3) {
;   for (int r = 0; r < 16; ++r) p1[r] = __builtin_amdgcn_exp2f(p1[r]);
;   float ps = 0; for (int r = 0; r < 16; ++r) ps += p0[r]; for (int r = 0; r < 16; ++r) ps += p1[r];
;   { auto rr = __builtin_amdgcn_permlane32_swap(__float_as_uint(ps), __float_as_uint(ps), false, false);
;     ps = __uint_as_float(rr[0]) + __uint_as_float(rr[1]); }
;   l_reg = l_reg * alpha + ps;
;     ...
;   PK4(p0, 0, pa0); PK4(p0, 8, pa1); PK4(p1, 0, pa2); PK4(p1, 8, pa3);
;     ...
; }
; __device__ __forceinline__ void qkt(f32x16& p0, f32x16& p1, const char* Ks, const bf16x8* qr, const bf16x8* qs, const int* kb) {
;   p0 = f32x16{}; p1 = f32x16{};
; #pragma unroll
;   for (int d0 = 0; d0 < 12; ++d0) { const int off = kb[d0 & 3] + (d0 >> 2) * 128;
;     bf16x8 b0 = *reinterpret_cast<const bf16x8*>(Ks + off);
;     bf16x8 b1 = *reinterpret_cast<const bf16x8*>(Ks + off + 32 * 384);
;     const bf16x8 q = d0 < 8 ? qr[d0 < 8 ? d0 : 0] : qs[(d0 - 8) * 64];
;     p0 = __builtin_amdgcn_mfma_f32_32x32x16_bf16(b0, q, p0, 0, 0, 0);
;     p1 = __builtin_amdgcn_mfma_f32_32x32x16_bf16(b1, q, p1, 0, 0, 0); }
.LBB0_107:
	s_mul_i32 s0, s49, 0x6000
	v_add_u32_e32 v250, s0, v173
	v_add_u32_e32 v251, s0, v181
	v_add_u32_e32 v252, s0, v182
	v_add_u32_e32 v172, s0, v183
	v_lshl_add_u32 v246, s8, 14, v171
	ds_read_b128 v[210:213], v250 offset:49152
	ds_read_b128 v[214:217], v250 offset:61440
	ds_read_b128 v[218:221], v251 offset:49152
	ds_read_b128 v[222:225], v251 offset:61440
	v_cvt_pk_bf16_f32 v188, v80, v81
	v_cvt_pk_bf16_f32 v189, v82, v83
	v_cvt_pk_bf16_f32 v190, v84, v85
	v_cvt_pk_bf16_f32 v191, v86, v87
	v_cvt_pk_bf16_f32 v192, v88, v89
	v_cvt_pk_bf16_f32 v193, v90, v91
	v_cvt_pk_bf16_f32 v194, v92, v93
	v_cvt_pk_bf16_f32 v195, v94, v95
	s_waitcnt lgkmcnt(2)
	v_mfma_f32_32x32x16_bf16 v[144:159], v[210:213], v[96:99], 0
	v_permlane32_swap_b32_e32 v188, v190
	v_permlane32_swap_b32_e32 v189, v191
	v_exp_f32_e32 v64, v64
	v_mfma_f32_32x32x16_bf16 v[128:143], v[214:217], v[96:99], 0
	ds_read_b128 v[210:213], v252 offset:49152
	ds_read_b128 v[214:217], v252 offset:61440
	v_permlane32_swap_b32_e32 v192, v194
	v_permlane32_swap_b32_e32 v193, v195
	v_exp_f32_e32 v65, v65
	s_waitcnt lgkmcnt(2)
	v_mfma_f32_32x32x16_bf16 v[144:159], v[218:221], v[100:103], v[144:159]
	v_add_f32_e32 v255, v80, v81
	v_add_f32_e32 v255, v82, v255
	v_exp_f32_e32 v66, v66
	v_mfma_f32_32x32x16_bf16 v[128:143], v[222:225], v[100:103], v[128:143]
	ds_read_b128 v[218:221], v172 offset:49152
	ds_read_b128 v[222:225], v172 offset:61440
	v_add_f32_e32 v255, v83, v255
	v_add_f32_e32 v255, v84, v255
	v_exp_f32_e32 v67, v67
	s_waitcnt lgkmcnt(2)
	v_mfma_f32_32x32x16_bf16 v[144:159], v[210:213], v[104:107], v[144:159]
	v_add_f32_e32 v255, v85, v255
	v_add_f32_e32 v255, v86, v255
	v_exp_f32_e32 v68, v68
	v_mfma_f32_32x32x16_bf16 v[128:143], v[214:217], v[104:107], v[128:143]
	ds_read_b128 v[210:213], v250 offset:49280
	ds_read_b128 v[214:217], v250 offset:61568
	v_add_f32_e32 v255, v87, v255
	v_add_f32_e32 v255, v88, v255
	v_exp_f32_e32 v69, v69
	s_waitcnt lgkmcnt(2)
	v_mfma_f32_32x32x16_bf16 v[144:159], v[218:221], v[116:119], v[144:159]
	v_add_f32_e32 v255, v89, v255
	v_add_f32_e32 v255, v90, v255
	v_exp_f32_e32 v70, v70
	v_mfma_f32_32x32x16_bf16 v[128:143], v[222:225], v[116:119], v[128:143]
	ds_read_b128 v[218:221], v251 offset:49280
	ds_read_b128 v[222:225], v251 offset:61568
	v_add_f32_e32 v255, v91, v255
	v_add_f32_e32 v255, v92, v255
	v_exp_f32_e32 v71, v71
	s_waitcnt lgkmcnt(2)
	v_mfma_f32_32x32x16_bf16 v[144:159], v[210:213], v[108:111], v[144:159]
	v_add_f32_e32 v255, v93, v255
	v_add_f32_e32 v255, v94, v255
	v_mfma_f32_32x32x16_bf16 v[128:143], v[214:217], v[108:111], v[128:143]
	ds_read_b128 v[210:213], v252 offset:49280
	ds_read_b128 v[214:217], v252 offset:61568
	v_exp_f32_e32 v72, v72
	v_add_f32_e32 v255, v95, v255
	v_cvt_pk_bf16_f32 v196, v64, v65
	s_cmp_lt_u32 s10, s42
	s_cselect_b32 s0, s44, s45
	s_ashr_i32 s1, s0, 31
	s_add_u32 s0, s10, s0
	s_addc_u32 s1, s11, s1
	v_lshl_add_u64 v[80:81], s[0:1], 0, v[162:163]
	v_lshlrev_b64 v[80:81], 11, v[80:81]
	v_lshl_add_u64 v[88:89], v[164:165], 0, v[80:81]
	v_add_co_u32_e32 v92, vcc, s73, v88
	s_lshl_b64 s[0:1], s[0:1], 7
	s_nop 0
	v_addc_co_u32_e32 v93, vcc, 0, v89, vcc
	v_lshl_add_u64 v[204:205], v[166:167], 0, s[0:1]
	s_waitcnt lgkmcnt(2)
	v_mfma_f32_32x32x16_bf16 v[144:159], v[218:221], v[112:115], v[144:159]
	v_cvt_pk_bf16_f32 v197, v66, v67
	v_cvt_pk_bf16_f32 v198, v68, v69
	v_cvt_pk_bf16_f32 v199, v70, v71
	v_add_f32_e32 v203, v64, v65
	global_load_dwordx4 v[80:83], v[88:89], off
	global_load_dwordx4 v[84:87], v[88:89], off offset:256
	s_nop 0
	global_load_dwordx4 v[88:91], v[92:93], off
	global_load_dwordx4 v[92:95], v[92:93], off offset:256
	global_load_dwordx4 v[204:207], v[204:205], off
	v_mfma_f32_32x32x16_bf16 v[128:143], v[222:225], v[112:115], v[128:143]
	ds_read_b128 v[218:221], v172 offset:49280
	ds_read_b128 v[222:225], v172 offset:61568
	v_add_f32_e32 v203, v66, v203
	v_exp_f32_e32 v73, v73
	v_add_f32_e32 v203, v67, v203
	s_waitcnt lgkmcnt(2)
	v_mfma_f32_32x32x16_bf16 v[144:159], v[210:213], v[120:123], v[144:159]
	v_add_f32_e32 v203, v68, v203
	v_exp_f32_e32 v74, v74
	v_add_f32_e32 v203, v69, v203
	v_mfma_f32_32x32x16_bf16 v[128:143], v[214:217], v[120:123], v[128:143]
	ds_read_b128 v[210:213], v250 offset:49408
	ds_read_b128 v[214:217], v250 offset:61696
	v_add_f32_e32 v203, v70, v203
	v_exp_f32_e32 v75, v75
	s_waitcnt lgkmcnt(2)
	v_mfma_f32_32x32x16_bf16 v[144:159], v[218:221], v[124:127], v[144:159]
	v_add_f32_e32 v203, v71, v203
	v_add_f32_e32 v203, v72, v203
	v_exp_f32_e32 v76, v76
	v_mfma_f32_32x32x16_bf16 v[128:143], v[222:225], v[124:127], v[128:143]
	ds_read_b128 v[218:221], v251 offset:49408
	ds_read_b128 v[222:225], v251 offset:61696
	v_permlane32_swap_b32_e32 v196, v198
	v_permlane32_swap_b32_e32 v197, v199
	v_exp_f32_e32 v77, v77
	s_waitcnt lgkmcnt(2)
	v_mfma_f32_32x32x16_bf16 v[144:159], v[210:213], v[226:229], v[144:159]
	v_add_f32_e32 v203, v73, v203
	v_add_f32_e32 v203, v74, v203
	v_exp_f32_e32 v78, v78
	v_mfma_f32_32x32x16_bf16 v[128:143], v[214:217], v[226:229], v[128:143]
	ds_read_b128 v[210:213], v252 offset:49408
	ds_read_b128 v[214:217], v252 offset:61696
	v_add_f32_e32 v203, v75, v203
	v_add_f32_e32 v203, v76, v203
	v_exp_f32_e32 v79, v79
	s_waitcnt lgkmcnt(2)
	v_mfma_f32_32x32x16_bf16 v[144:159], v[218:221], v[230:233], v[144:159]
	v_add_f32_e32 v203, v77, v203
	v_add_f32_e32 v203, v78, v203
	v_add_f32_e32 v203, v79, v203
	v_mfma_f32_32x32x16_bf16 v[128:143], v[222:225], v[230:233], v[128:143]
	ds_read_b128 v[218:221], v172 offset:49408
	ds_read_b128 v[222:225], v172 offset:61696
	v_add_f32_e32 v255, v255, v203
	v_mov_b32_e32 v202, v255
	s_nop 1
	v_permlane32_swap_b32_e32 v255, v202
	v_add_f32_e32 v255, v255, v202
	s_waitcnt lgkmcnt(2)
; #define PV_WAIT(n, f) asm volatile("s_waitcnt lgkmcnt(" #n ")" : "+v"(f[0]), "+v"(f[1]), "+v"(f[2]), "+v"(f[3]), "+v"(f[4]), "+v"(f[5]), "+v"(f[6]), "+v"(f[7]))
; __device__ __forceinline__ void partialSM(f32x16& p0, f32x16& p1, float& m_reg, float& mn, float& alpha) {
;   constexpr float C = SCALE * 1.4426950408889634f;
;   float pmax = p0[0]; for (int r = 1; r < 16; ++r) pmax = fmaxf(pmax, p0[r]); for (int r = 0; r < 16; ++r) pmax = fmaxf(pmax, p1[r]);
;   { auto rr = __builtin_amdgcn_permlane32_swap(__float_as_uint(pmax), __float_as_uint(pmax), false, false);
;     pmax = fmaxf(__uint_as_float(rr[0]), __uint_as_float(rr[1])); }
;   if (__builtin_expect(__all(pmax - m_reg <= THR / SCALE), 1)) { mn = m_reg; alpha = 1.f; }
;   else { mn = fmaxf(m_reg, pmax); alpha = __builtin_amdgcn_exp2f((m_reg - mn) * C); m_reg = mn; }
;   float mnC = -mn * C;
;   for (int r = 0; r < 16; ++r) p0[r] = fmaf(p0[r], C, mnC); for (int r = 0; r < 16; ++r) p1[r] = fmaf(p1[r], C, mnC);
;   for (int r = 0; r < 16; ++r) p0[r] = __builtin_amdgcn_exp2f(p0[r]);
; }
; __device__ __forceinline__ void pv_d0(f32x16* o, int vb, bf16x8 pa0, bf16x8 pa1, bf16x8 pa2, bf16x8 pa3) {
;   s16x4 fa[8], fb[8];
;   pv_rd<0>(fa, vb); pv_rd<1>(fb, vb);
;   PV_WAIT(8, fa); pv_mm(o[0], fa, pa0, pa1, pa2, pa3);
;   pv_rd<2>(fa, vb);
;   PV_WAIT(8, fb); pv_mm(o[1], fb, pa0, pa1, pa2, pa3);
;   pv_rd<3>(fb, vb);
;   PV_WAIT(8, fa); pv_mm(o[2], fa, pa0, pa1, pa2, pa3);
;   PV_WAIT(0, fb); pv_mm(o[3], fb, pa0, pa1, pa2, pa3);
; }
	v_mfma_f32_32x32x16_bf16 v[144:159], v[210:213], v[234:237], v[144:159]
	v_fma_f32 v170, v170, v249, v255
	v_cvt_pk_bf16_f32 v200, v72, v73
	v_cvt_pk_bf16_f32 v201, v74, v75
	v_cvt_pk_bf16_f32 v202, v76, v77
	v_mfma_f32_32x32x16_bf16 v[128:143], v[214:217], v[234:237], v[128:143]
	ds_read_b64_tr_b16 v[210:211], v246 offset:0
	ds_read_b64_tr_b16 v[212:213], v246 offset:2048
	ds_read_b64_tr_b16 v[214:215], v246 offset:4096
	ds_read_b64_tr_b16 v[216:217], v246 offset:6144
	v_cvt_pk_bf16_f32 v203, v78, v79
	v_permlane32_swap_b32_e32 v200, v202
	s_nop 0
	v_permlane32_swap_b32_e32 v201, v203
	s_waitcnt lgkmcnt(4)
	v_mfma_f32_32x32x16_bf16 v[144:159], v[218:221], v[238:241], v[144:159]
	v_mfma_f32_32x32x16_bf16 v[128:143], v[222:225], v[238:241], v[128:143]
	ds_read_b64_tr_b16 v[218:219], v246 offset:8192
	ds_read_b64_tr_b16 v[220:221], v246 offset:10240
	ds_read_b64_tr_b16 v[222:223], v246 offset:12288
	ds_read_b64_tr_b16 v[224:225], v246 offset:14336
	ds_read_b64_tr_b16 v[184:185], v246 offset:512
	ds_read_b64_tr_b16 v[186:187], v246 offset:2560
	s_lshl_b32 s14, s9, 14
	s_lshl_b32 s1, s9, 13
	s_add_i32 s15, s14, s1
	s_waitcnt lgkmcnt(6)
	v_mfma_f32_32x32x16_bf16 v[0:15], v[188:191], v[210:213], v[0:15]
	ds_read_b64_tr_b16 v[210:211], v246 offset:4608
	ds_read_b64_tr_b16 v[212:213], v246 offset:6656
	v_max3_f32 v64, v144, v145, v146
	v_max3_f32 v65, v128, v129, v130
	v_max3_f32 v64, v64, v147, v148
	v_max3_f32 v65, v65, v131, v132
	v_max3_f32 v64, v64, v149, v150
	v_max3_f32 v65, v65, v133, v134
	v_mfma_f32_32x32x16_bf16 v[0:15], v[192:195], v[214:217], v[0:15]
	ds_read_b64_tr_b16 v[214:215], v246 offset:8704
	ds_read_b64_tr_b16 v[216:217], v246 offset:10752
	v_max3_f32 v64, v64, v151, v152
	v_max3_f32 v65, v65, v135, v136
	v_max3_f32 v64, v64, v153, v154
	v_max3_f32 v65, v65, v137, v138
	v_max3_f32 v64, v64, v155, v156
	v_max3_f32 v65, v65, v139, v140
	s_waitcnt lgkmcnt(6)
	v_mfma_f32_32x32x16_bf16 v[0:15], v[196:199], v[218:221], v[0:15]
	ds_read_b64_tr_b16 v[218:219], v246 offset:12800
	ds_read_b64_tr_b16 v[220:221], v246 offset:14848
	v_max3_f32 v64, v64, v157, v158
	v_max3_f32 v65, v65, v141, v142
	v_max_f32_e32 v64, v64, v159
	v_max_f32_e32 v65, v65, v143
	v_max_f32_e32 v64, v64, v65
	v_mov_b32_e32 v66, v64
	v_mfma_f32_32x32x16_bf16 v[0:15], v[200:203], v[222:225], v[0:15]
	ds_read_b64_tr_b16 v[222:223], v246 offset:1024
	ds_read_b64_tr_b16 v[224:225], v246 offset:3072
	v_permlane32_swap_b32_e32 v64, v66
	v_max_f32_e32 v64, v64, v66
	v_sub_f32_e32 v67, v64, v178
	v_cmp_ge_f32_e32 vcc, s74, v67
	v_max_f32_e32 v68, v178, v64
	v_sub_f32_e32 v67, v178, v68
	s_waitcnt lgkmcnt(6)
	v_mfma_f32_32x32x16_bf16 v[48:63], v[188:191], v[184:187], v[48:63]
	ds_read_b64_tr_b16 v[184:185], v246 offset:5120
	ds_read_b64_tr_b16 v[186:187], v246 offset:7168
	v_mul_f32_e32 v67, 0x3dd53b94, v67
	v_exp_f32_e32 v67, v67
	s_cmp_eq_u64 vcc, exec
	s_cselect_b64 s[6:7], -1, 0
	v_cndmask_b32_e64 v249, v67, 1.0, s[6:7]
	v_cndmask_b32_e64 v178, v68, v178, s[6:7]
	v_mfma_f32_32x32x16_bf16 v[48:63], v[192:195], v[210:213], v[48:63]
	ds_read_b64_tr_b16 v[210:211], v246 offset:9216
	ds_read_b64_tr_b16 v[212:213], v246 offset:11264
	v_mul_f32_e32 v69, 0xbdd53b94, v178
	v_cmp_gt_f32_e32 vcc, 1.0, v249
	v_fmamk_f32 v144, v144, 0x3dd53b94, v69
	v_fmamk_f32 v145, v145, 0x3dd53b94, v69
	v_fmamk_f32 v146, v146, 0x3dd53b94, v69
	v_fmamk_f32 v147, v147, 0x3dd53b94, v69
	s_waitcnt lgkmcnt(6)
	v_mfma_f32_32x32x16_bf16 v[48:63], v[196:199], v[214:217], v[48:63]
	ds_read_b64_tr_b16 v[214:215], v246 offset:13312
	ds_read_b64_tr_b16 v[216:217], v246 offset:15360
	v_fmamk_f32 v148, v148, 0x3dd53b94, v69
	v_fmamk_f32 v149, v149, 0x3dd53b94, v69
	v_fmamk_f32 v150, v150, 0x3dd53b94, v69
	v_fmamk_f32 v151, v151, 0x3dd53b94, v69
	v_fmamk_f32 v152, v152, 0x3dd53b94, v69
	v_exp_f32_e32 v144, v144
	v_mfma_f32_32x32x16_bf16 v[48:63], v[200:203], v[218:221], v[48:63]
	ds_read_b64_tr_b16 v[218:219], v246 offset:1536
	ds_read_b64_tr_b16 v[220:221], v246 offset:3584
	v_fmamk_f32 v153, v153, 0x3dd53b94, v69
	v_exp_f32_e32 v145, v145
	v_fmamk_f32 v154, v154, 0x3dd53b94, v69
	v_exp_f32_e32 v146, v146
	s_waitcnt lgkmcnt(6)
	v_mfma_f32_32x32x16_bf16 v[32:47], v[188:191], v[222:225], v[32:47]
	ds_read_b64_tr_b16 v[222:223], v246 offset:5632
	ds_read_b64_tr_b16 v[224:225], v246 offset:7680
	v_fmamk_f32 v155, v155, 0x3dd53b94, v69
	v_exp_f32_e32 v147, v147
	v_fmamk_f32 v156, v156, 0x3dd53b94, v69
	v_exp_f32_e32 v148, v148
	v_mfma_f32_32x32x16_bf16 v[32:47], v[192:195], v[184:187], v[32:47]
	ds_read_b64_tr_b16 v[184:185], v246 offset:9728
	ds_read_b64_tr_b16 v[186:187], v246 offset:11776
	v_fmamk_f32 v157, v157, 0x3dd53b94, v69
	v_exp_f32_e32 v149, v149
	v_fmamk_f32 v158, v158, 0x3dd53b94, v69
	v_exp_f32_e32 v150, v150
	s_waitcnt lgkmcnt(6)
	v_mfma_f32_32x32x16_bf16 v[32:47], v[196:199], v[210:213], v[32:47]
	ds_read_b64_tr_b16 v[210:211], v246 offset:13824
	ds_read_b64_tr_b16 v[212:213], v246 offset:15872
	v_fmamk_f32 v159, v159, 0x3dd53b94, v69
	v_exp_f32_e32 v151, v151
	v_fmamk_f32 v128, v128, 0x3dd53b94, v69
	v_fmamk_f32 v129, v129, 0x3dd53b94, v69
	v_add_u32_e32 v70, s14, v174
	s_waitcnt vmcnt(3)
	ds_write_b128 v70, v[84:87]
	v_mfma_f32_32x32x16_bf16 v[32:47], v[200:203], v[214:217], v[32:47]
	v_exp_f32_e32 v152, v152
	v_fmamk_f32 v130, v130, 0x3dd53b94, v69
	v_fmamk_f32 v131, v131, 0x3dd53b94, v69
	v_exp_f32_e32 v153, v153
	v_add_u32_e32 v71, s14, v175
	s_waitcnt vmcnt(1)
	ds_write_b128 v71, v[92:95]
	s_waitcnt lgkmcnt(6)
	v_mfma_f32_32x32x16_bf16 v[16:31], v[188:191], v[218:221], v[16:31]
	v_fmamk_f32 v132, v132, 0x3dd53b94, v69
	v_fmamk_f32 v133, v133, 0x3dd53b94, v69
	v_exp_f32_e32 v154, v154
	v_fmamk_f32 v134, v134, 0x3dd53b94, v69
	v_fmamk_f32 v135, v135, 0x3dd53b94, v69
	v_add_u32_e32 v70, s15, v179
	ds_write_b128 v70, v[80:83] offset:49152
	ds_write_b128 v70, v[88:91] offset:61440
	v_mfma_f32_32x32x16_bf16 v[16:31], v[192:195], v[222:225], v[16:31]
	v_exp_f32_e32 v155, v155
	v_fmamk_f32 v136, v136, 0x3dd53b94, v69
	v_fmamk_f32 v137, v137, 0x3dd53b94, v69
	v_exp_f32_e32 v156, v156
	v_add_u32_e32 v71, s15, v180
	s_waitcnt vmcnt(0)
	ds_write_b128 v71, v[204:207] offset:49152
	s_waitcnt lgkmcnt(5)
	v_mfma_f32_32x32x16_bf16 v[16:31], v[196:199], v[184:187], v[16:31]
	v_fmamk_f32 v138, v138, 0x3dd53b94, v69
	v_fmamk_f32 v139, v139, 0x3dd53b94, v69
	v_exp_f32_e32 v157, v157
	v_fmamk_f32 v140, v140, 0x3dd53b94, v69
	v_fmamk_f32 v141, v141, 0x3dd53b94, v69
	v_mfma_f32_32x32x16_bf16 v[16:31], v[200:203], v[210:213], v[16:31]
	v_exp_f32_e32 v158, v158
	v_fmamk_f32 v142, v142, 0x3dd53b94, v69
	v_fmamk_f32 v143, v143, 0x3dd53b94, v69
	v_exp_f32_e32 v159, v159
	s_cbranch_vccz .Lattn_skip1
; #define SBAR() __builtin_amdgcn_sched_barrier(0)
; #define SLOAD(k0) do { const long rb = KROW(k0); const bf16* pn = KN + (rb + sr) * LDKN + sc; \
;     ks0 = *reinterpret_cast<const bf16x8*>(pn); ks1 = *reinterpret_cast<const bf16x8*>(pn + 32 * LDKN); vs0 = *reinterpret_cast<const bf16x8*>(pn + 128); vs1 = *reinterpret_cast<const bf16x8*>(pn + 32 * LDKN + 128); \
;     ks2 = *reinterpret_cast<const bf16x8*>(KR + rb * LDKR + tid * 8); } while (0)
; #define RESC(a) do { if (__any((a) < 1.f)) { if (hi == 0) al_l[r32] = (a); asm volatile("s_waitcnt lgkmcnt(0)" ::: "memory"); \
;     for (int d = 0; d < 4; ++d) for (int r = 0; r < 16; ++r) o[d][r] *= al_l[crow(r, hi)]; } } while (0)
; __device__ __forceinline__ void attn_unit(const bf16* __restrict__ Qb, const bf16* __restrict__ KN, const bf16* __restrict__ KR, ...
;     ...
;     RESC(alB); __syncthreads();
;     { const int t = rp; rp = rc; rc = rn; rn = t; }
;     SBAR(); qkt(pA0, pA1, K_lds + rc * SHM_K, qr, qs, kb);
;     finishSM(pB0, pB1, alB, l_reg, pa0, pa1, pa2, pa3); SBAR();
;     SLOAD((j + 2) * KVBLK); SBAR();
;     pv_d0(o, vb0 + rp * SHM_V, pa0, pa1, pa2, pa3); partialSM(pA0, pA1, m_reg, mnA, alA);
	s_and_saveexec_b64 s[12:13], s[4:5]
	ds_write_b32 v169, v249 offset:128
	s_or_b64 exec, exec, s[12:13]
	s_waitcnt lgkmcnt(0)
	v_add_u32_e32 v250, v168, v208
	ds_read_b128 v[64:67], v250 offset:128
	ds_read_b128 v[68:71], v250 offset:160
	ds_read_b128 v[72:75], v250 offset:192
	ds_read_b128 v[76:79], v250 offset:224
	s_waitcnt lgkmcnt(0)
	v_pk_mul_f32 v[0:1], v[0:1], v[64:65]
	v_pk_mul_f32 v[2:3], v[2:3], v[66:67]
	v_pk_mul_f32 v[4:5], v[4:5], v[68:69]
	v_pk_mul_f32 v[6:7], v[6:7], v[70:71]
	v_pk_mul_f32 v[8:9], v[8:9], v[72:73]
	v_pk_mul_f32 v[10:11], v[10:11], v[74:75]
	v_pk_mul_f32 v[12:13], v[12:13], v[76:77]
	v_pk_mul_f32 v[14:15], v[14:15], v[78:79]
	v_pk_mul_f32 v[48:49], v[48:49], v[64:65]
	v_pk_mul_f32 v[50:51], v[50:51], v[66:67]
	v_pk_mul_f32 v[52:53], v[52:53], v[68:69]
	v_pk_mul_f32 v[54:55], v[54:55], v[70:71]
	v_pk_mul_f32 v[56:57], v[56:57], v[72:73]
	v_pk_mul_f32 v[58:59], v[58:59], v[74:75]
	v_pk_mul_f32 v[60:61], v[60:61], v[76:77]
	v_pk_mul_f32 v[62:63], v[62:63], v[78:79]
	v_pk_mul_f32 v[32:33], v[32:33], v[64:65]
	v_pk_mul_f32 v[34:35], v[34:35], v[66:67]
	v_pk_mul_f32 v[36:37], v[36:37], v[68:69]
	v_pk_mul_f32 v[38:39], v[38:39], v[70:71]
	v_pk_mul_f32 v[40:41], v[40:41], v[72:73]
	v_pk_mul_f32 v[42:43], v[42:43], v[74:75]
	v_pk_mul_f32 v[44:45], v[44:45], v[76:77]
	v_pk_mul_f32 v[46:47], v[46:47], v[78:79]
	v_pk_mul_f32 v[16:17], v[16:17], v[64:65]
	v_pk_mul_f32 v[18:19], v[18:19], v[66:67]
	v_pk_mul_f32 v[20:21], v[20:21], v[68:69]
	v_pk_mul_f32 v[22:23], v[22:23], v[70:71]
	v_pk_mul_f32 v[24:25], v[24:25], v[72:73]
	v_pk_mul_f32 v[26:27], v[26:27], v[74:75]
	v_pk_mul_f32 v[28:29], v[28:29], v[76:77]
	v_pk_mul_f32 v[30:31], v[30:31], v[78:79]
.Lattn_skip1:
	s_waitcnt lgkmcnt(0)
	s_barrier
	s_mul_i32 s0, s9, 0x6000
	v_add_u32_e32 v250, s0, v173
	v_add_u32_e32 v251, s0, v181
	v_add_u32_e32 v252, s0, v182
	v_add_u32_e32 v172, s0, v183
	v_lshl_add_u32 v246, s49, 14, v171
	ds_read_b128 v[210:213], v250 offset:49152
	ds_read_b128 v[214:217], v250 offset:61440
	ds_read_b128 v[218:221], v251 offset:49152
	ds_read_b128 v[222:225], v251 offset:61440
	v_cvt_pk_bf16_f32 v188, v144, v145
	v_cvt_pk_bf16_f32 v189, v146, v147
	v_cvt_pk_bf16_f32 v190, v148, v149
	v_cvt_pk_bf16_f32 v191, v150, v151
	v_cvt_pk_bf16_f32 v192, v152, v153
	v_cvt_pk_bf16_f32 v193, v154, v155
	v_cvt_pk_bf16_f32 v194, v156, v157
	v_cvt_pk_bf16_f32 v195, v158, v159
	s_waitcnt lgkmcnt(2)
	v_mfma_f32_32x32x16_bf16 v[80:95], v[210:213], v[96:99], 0
	v_permlane32_swap_b32_e32 v188, v190
	v_permlane32_swap_b32_e32 v189, v191
	v_exp_f32_e32 v128, v128
	v_mfma_f32_32x32x16_bf16 v[64:79], v[214:217], v[96:99], 0
	ds_read_b128 v[210:213], v252 offset:49152
	ds_read_b128 v[214:217], v252 offset:61440
	v_permlane32_swap_b32_e32 v192, v194
	v_permlane32_swap_b32_e32 v193, v195
	v_exp_f32_e32 v129, v129
	s_waitcnt lgkmcnt(2)
	v_mfma_f32_32x32x16_bf16 v[80:95], v[218:221], v[100:103], v[80:95]
	v_add_f32_e32 v255, v144, v145
	v_add_f32_e32 v255, v146, v255
	v_exp_f32_e32 v130, v130
	v_mfma_f32_32x32x16_bf16 v[64:79], v[222:225], v[100:103], v[64:79]
	ds_read_b128 v[218:221], v172 offset:49152
	ds_read_b128 v[222:225], v172 offset:61440
	v_add_f32_e32 v255, v147, v255
	v_add_f32_e32 v255, v148, v255
	v_exp_f32_e32 v131, v131
	s_waitcnt lgkmcnt(2)
	v_mfma_f32_32x32x16_bf16 v[80:95], v[210:213], v[104:107], v[80:95]
	v_add_f32_e32 v255, v149, v255
	v_add_f32_e32 v255, v150, v255
	v_exp_f32_e32 v132, v132
	v_mfma_f32_32x32x16_bf16 v[64:79], v[214:217], v[104:107], v[64:79]
	ds_read_b128 v[210:213], v250 offset:49280
	ds_read_b128 v[214:217], v250 offset:61568
	v_add_f32_e32 v255, v151, v255
	v_add_f32_e32 v255, v152, v255
	v_exp_f32_e32 v133, v133
	s_waitcnt lgkmcnt(2)
	v_mfma_f32_32x32x16_bf16 v[80:95], v[218:221], v[116:119], v[80:95]
	v_add_f32_e32 v255, v153, v255
	v_add_f32_e32 v255, v154, v255
	v_exp_f32_e32 v134, v134
	v_mfma_f32_32x32x16_bf16 v[64:79], v[222:225], v[116:119], v[64:79]
	ds_read_b128 v[218:221], v251 offset:49280
	ds_read_b128 v[222:225], v251 offset:61568
	v_add_f32_e32 v255, v155, v255
	v_add_f32_e32 v255, v156, v255
	v_exp_f32_e32 v135, v135
	s_waitcnt lgkmcnt(2)
	v_mfma_f32_32x32x16_bf16 v[80:95], v[210:213], v[108:111], v[80:95]
	v_add_f32_e32 v255, v157, v255
	v_add_f32_e32 v255, v158, v255
	v_mfma_f32_32x32x16_bf16 v[64:79], v[214:217], v[108:111], v[64:79]
	ds_read_b128 v[210:213], v252 offset:49280
	ds_read_b128 v[214:217], v252 offset:61568
	v_exp_f32_e32 v136, v136
	v_add_f32_e32 v255, v159, v255
	v_cvt_pk_bf16_f32 v196, v128, v129
	s_add_i32 s0, s10, 64
	s_cmp_lt_u32 s0, s42
	s_cselect_b32 s1, s44, s45
	s_add_i32 s0, s0, s1
	s_ashr_i32 s1, s0, 31
	v_lshl_add_u64 v[144:145], s[0:1], 0, v[162:163]
	v_lshlrev_b64 v[144:145], 11, v[144:145]
	v_lshl_add_u64 v[152:153], v[164:165], 0, v[144:145]
	v_add_co_u32_e32 v156, vcc, s73, v152
	s_lshl_b64 s[0:1], s[0:1], 7
	s_nop 0
	v_addc_co_u32_e32 v157, vcc, 0, v153, vcc
	v_lshl_add_u64 v[204:205], v[166:167], 0, s[0:1]
	s_waitcnt lgkmcnt(2)
	v_mfma_f32_32x32x16_bf16 v[80:95], v[218:221], v[112:115], v[80:95]
	v_cvt_pk_bf16_f32 v197, v130, v131
	v_cvt_pk_bf16_f32 v198, v132, v133
	v_cvt_pk_bf16_f32 v199, v134, v135
	v_add_f32_e32 v203, v128, v129
	global_load_dwordx4 v[144:147], v[152:153], off
	global_load_dwordx4 v[148:151], v[152:153], off offset:256
	s_nop 0
	global_load_dwordx4 v[152:155], v[156:157], off
	global_load_dwordx4 v[156:159], v[156:157], off offset:256
	global_load_dwordx4 v[204:207], v[204:205], off
	v_mfma_f32_32x32x16_bf16 v[64:79], v[222:225], v[112:115], v[64:79]
	ds_read_b128 v[218:221], v172 offset:49280
	ds_read_b128 v[222:225], v172 offset:61568
	v_add_f32_e32 v203, v130, v203
	v_exp_f32_e32 v137, v137
	v_add_f32_e32 v203, v131, v203
	s_waitcnt lgkmcnt(2)
; #define PV_WAIT(n, f) asm volatile("s_waitcnt lgkmcnt(" #n ")" : "+v"(f[0]), "+v"(f[1]), "+v"(f[2]), "+v"(f[3]), "+v"(f[4]), "+v"(f[5]), "+v"(f[6]), "+v"(f[7]))
; __device__ __forceinline__ void partialSM(f32x16& p0, f32x16& p1, float& m_reg, float& mn, float& alpha) {
;   constexpr float C = SCALE * 1.4426950408889634f;
;   float pmax = p0[0]; for (int r = 1; r < 16; ++r) pmax = fmaxf(pmax, p0[r]); for (int r = 0; r < 16; ++r) pmax = fmaxf(pmax, p1[r]);
;   { auto rr = __builtin_amdgcn_permlane32_swap(__float_as_uint(pmax), __float_as_uint(pmax), false, false);
;     pmax = fmaxf(__uint_as_float(rr[0]), __uint_as_float(rr[1])); }
;   if (__builtin_expect(__all(pmax - m_reg <= THR / SCALE), 1)) { mn = m_reg; alpha = 1.f; }
;   else { mn = fmaxf(m_reg, pmax); alpha = __builtin_amdgcn_exp2f((m_reg - mn) * C); m_reg = mn; }
;   float mnC = -mn * C;
;   for (int r = 0; r < 16; ++r) p0[r] = fmaf(p0[r], C, mnC); for (int r = 0; r < 16; ++r) p1[r] = fmaf(p1[r], C, mnC);
;   for (int r = 0; r < 16; ++r) p0[r] = __builtin_amdgcn_exp2f(p0[r]);
; }
; __device__ __forceinline__ void pv_d0(f32x16* o, int vb, bf16x8 pa0, bf16x8 pa1, bf16x8 pa2, bf16x8 pa3) {
;   s16x4 fa[8], fb[8];
;   pv_rd<0>(fa, vb); pv_rd<1>(fb, vb);
;   PV_WAIT(8, fa); pv_mm(o[0], fa, pa0, pa1, pa2, pa3);
;   pv_rd<2>(fa, vb);
;   PV_WAIT(8, fb); pv_mm(o[1], fb, pa0, pa1, pa2, pa3);
;   pv_rd<3>(fb, vb);
;   PV_WAIT(8, fa); pv_mm(o[2], fa, pa0, pa1, pa2, pa3);
;   PV_WAIT(0, fb); pv_mm(o[3], fb, pa0, pa1, pa2, pa3);
; }
	v_mfma_f32_32x32x16_bf16 v[80:95], v[210:213], v[120:123], v[80:95]
	v_add_f32_e32 v203, v132, v203
	v_exp_f32_e32 v138, v138
	v_add_f32_e32 v203, v133, v203
	v_mfma_f32_32x32x16_bf16 v[64:79], v[214:217], v[120:123], v[64:79]
	ds_read_b128 v[210:213], v250 offset:49408
	ds_read_b128 v[214:217], v250 offset:61696
	v_add_f32_e32 v203, v134, v203
	v_exp_f32_e32 v139, v139
	s_waitcnt lgkmcnt(2)
	v_mfma_f32_32x32x16_bf16 v[80:95], v[218:221], v[124:127], v[80:95]
	v_add_f32_e32 v203, v135, v203
	v_add_f32_e32 v203, v136, v203
	v_exp_f32_e32 v140, v140
	v_mfma_f32_32x32x16_bf16 v[64:79], v[222:225], v[124:127], v[64:79]
	ds_read_b128 v[218:221], v251 offset:49408
	ds_read_b128 v[222:225], v251 offset:61696
	v_permlane32_swap_b32_e32 v196, v198
	v_permlane32_swap_b32_e32 v197, v199
	v_exp_f32_e32 v141, v141
	s_waitcnt lgkmcnt(2)
	v_mfma_f32_32x32x16_bf16 v[80:95], v[210:213], v[226:229], v[80:95]
	v_add_f32_e32 v203, v137, v203
	v_add_f32_e32 v203, v138, v203
	v_exp_f32_e32 v142, v142
	v_mfma_f32_32x32x16_bf16 v[64:79], v[214:217], v[226:229], v[64:79]
	ds_read_b128 v[210:213], v252 offset:49408
	ds_read_b128 v[214:217], v252 offset:61696
	v_add_f32_e32 v203, v139, v203
	v_add_f32_e32 v203, v140, v203
	v_exp_f32_e32 v143, v143
	s_waitcnt lgkmcnt(2)
	v_mfma_f32_32x32x16_bf16 v[80:95], v[218:221], v[230:233], v[80:95]
	v_add_f32_e32 v203, v141, v203
	v_add_f32_e32 v203, v142, v203
	v_add_f32_e32 v203, v143, v203
	v_mfma_f32_32x32x16_bf16 v[64:79], v[222:225], v[230:233], v[64:79]
	ds_read_b128 v[218:221], v172 offset:49408
	ds_read_b128 v[222:225], v172 offset:61696
	v_add_f32_e32 v255, v255, v203
	v_mov_b32_e32 v202, v255
	s_nop 1
	v_permlane32_swap_b32_e32 v255, v202
	v_add_f32_e32 v255, v255, v202
	s_waitcnt lgkmcnt(2)
	v_mfma_f32_32x32x16_bf16 v[80:95], v[210:213], v[234:237], v[80:95]
	v_fma_f32 v170, v170, v249, v255
	v_cvt_pk_bf16_f32 v200, v136, v137
	v_cvt_pk_bf16_f32 v201, v138, v139
	v_cvt_pk_bf16_f32 v202, v140, v141
	v_mfma_f32_32x32x16_bf16 v[64:79], v[214:217], v[234:237], v[64:79]
	ds_read_b64_tr_b16 v[210:211], v246 offset:0
	ds_read_b64_tr_b16 v[212:213], v246 offset:2048
	ds_read_b64_tr_b16 v[214:215], v246 offset:4096
	ds_read_b64_tr_b16 v[216:217], v246 offset:6144
	v_cvt_pk_bf16_f32 v203, v142, v143
	v_permlane32_swap_b32_e32 v200, v202
	s_nop 0
	v_permlane32_swap_b32_e32 v201, v203
	s_waitcnt lgkmcnt(4)
	v_mfma_f32_32x32x16_bf16 v[80:95], v[218:221], v[238:241], v[80:95]
	v_mfma_f32_32x32x16_bf16 v[64:79], v[222:225], v[238:241], v[64:79]
	ds_read_b64_tr_b16 v[218:219], v246 offset:8192
	ds_read_b64_tr_b16 v[220:221], v246 offset:10240
	ds_read_b64_tr_b16 v[222:223], v246 offset:12288
	ds_read_b64_tr_b16 v[224:225], v246 offset:14336
	ds_read_b64_tr_b16 v[184:185], v246 offset:512
	ds_read_b64_tr_b16 v[186:187], v246 offset:2560
	s_lshl_b32 s14, s8, 14
	s_lshl_b32 s1, s8, 13
	s_add_i32 s15, s14, s1
	s_waitcnt lgkmcnt(6)
	v_mfma_f32_32x32x16_bf16 v[0:15], v[188:191], v[210:213], v[0:15]
	ds_read_b64_tr_b16 v[210:211], v246 offset:4608
	ds_read_b64_tr_b16 v[212:213], v246 offset:6656
	v_max3_f32 v128, v80, v81, v82
	v_max3_f32 v129, v64, v65, v66
	v_max3_f32 v128, v128, v83, v84
	v_max3_f32 v129, v129, v67, v68
	v_max3_f32 v128, v128, v85, v86
	v_max3_f32 v129, v129, v69, v70
	v_mfma_f32_32x32x16_bf16 v[0:15], v[192:195], v[214:217], v[0:15]
	ds_read_b64_tr_b16 v[214:215], v246 offset:8704
	ds_read_b64_tr_b16 v[216:217], v246 offset:10752
	v_max3_f32 v128, v128, v87, v88
	v_max3_f32 v129, v129, v71, v72
	v_max3_f32 v128, v128, v89, v90
	v_max3_f32 v129, v129, v73, v74
	v_max3_f32 v128, v128, v91, v92
	v_max3_f32 v129, v129, v75, v76
	s_waitcnt lgkmcnt(6)
	v_mfma_f32_32x32x16_bf16 v[0:15], v[196:199], v[218:221], v[0:15]
	ds_read_b64_tr_b16 v[218:219], v246 offset:12800
	ds_read_b64_tr_b16 v[220:221], v246 offset:14848
	v_max3_f32 v128, v128, v93, v94
	v_max3_f32 v129, v129, v77, v78
	v_max_f32_e32 v128, v128, v95
	v_max_f32_e32 v129, v129, v79
	v_max_f32_e32 v128, v128, v129
	v_mov_b32_e32 v130, v128
	v_mfma_f32_32x32x16_bf16 v[0:15], v[200:203], v[222:225], v[0:15]
	ds_read_b64_tr_b16 v[222:223], v246 offset:1024
	ds_read_b64_tr_b16 v[224:225], v246 offset:3072
	v_permlane32_swap_b32_e32 v128, v130
	v_max_f32_e32 v128, v128, v130
	v_sub_f32_e32 v131, v128, v178
	v_cmp_ge_f32_e32 vcc, s74, v131
	v_max_f32_e32 v132, v178, v128
	v_sub_f32_e32 v131, v178, v132
	s_waitcnt lgkmcnt(6)
	v_mfma_f32_32x32x16_bf16 v[48:63], v[188:191], v[184:187], v[48:63]
	ds_read_b64_tr_b16 v[184:185], v246 offset:5120
	ds_read_b64_tr_b16 v[186:187], v246 offset:7168
	v_mul_f32_e32 v131, 0x3dd53b94, v131
	v_exp_f32_e32 v131, v131
	s_cmp_eq_u64 vcc, exec
	s_cselect_b64 s[6:7], -1, 0
	v_cndmask_b32_e64 v249, v131, 1.0, s[6:7]
	v_cndmask_b32_e64 v178, v132, v178, s[6:7]
	v_mfma_f32_32x32x16_bf16 v[48:63], v[192:195], v[210:213], v[48:63]
	ds_read_b64_tr_b16 v[210:211], v246 offset:9216
	ds_read_b64_tr_b16 v[212:213], v246 offset:11264
	v_mul_f32_e32 v133, 0xbdd53b94, v178
	v_cmp_gt_f32_e32 vcc, 1.0, v249
	v_fmamk_f32 v80, v80, 0x3dd53b94, v133
	v_fmamk_f32 v81, v81, 0x3dd53b94, v133
	v_fmamk_f32 v82, v82, 0x3dd53b94, v133
	v_fmamk_f32 v83, v83, 0x3dd53b94, v133
	s_waitcnt lgkmcnt(6)
; #define SWRITE(b) do { *(bf16x8*)(V_lds + (b) * SHM_V + vst0) = vs0; *(bf16x8*)(V_lds + (b) * SHM_V + vst1) = vs1; \
;     *(bf16x8*)(K_lds + (b) * SHM_K + knd0) = ks0; *(bf16x8*)(K_lds + (b) * SHM_K + knd1) = ks1; *(bf16x8*)(K_lds + (b) * SHM_K + krd) = ks2; } while (0)
; #define RESC(a) do { if (__any((a) < 1.f)) { if (hi == 0) al_l[r32] = (a); asm volatile("s_waitcnt lgkmcnt(0)" ::: "memory"); \
;     for (int d = 0; d < 4; ++d) for (int r = 0; r < 16; ++r) o[d][r] *= al_l[crow(r, hi)]; } } while (0)
; __device__ __forceinline__ void attn_unit(const bf16* __restrict__ Qb, const bf16* __restrict__ KN, const bf16* __restrict__ KR, ...
;     ...
;     pv_d0(o, vb0 + rp * SHM_V, pa0, pa1, pa2, pa3); partialSM(pA0, pA1, m_reg, mnA, alA);
;     SWRITE(rn);
;     RESC(alA); __syncthreads();
	v_mfma_f32_32x32x16_bf16 v[48:63], v[196:199], v[214:217], v[48:63]
	ds_read_b64_tr_b16 v[214:215], v246 offset:13312
	ds_read_b64_tr_b16 v[216:217], v246 offset:15360
	v_fmamk_f32 v84, v84, 0x3dd53b94, v133
	v_fmamk_f32 v85, v85, 0x3dd53b94, v133
	v_fmamk_f32 v86, v86, 0x3dd53b94, v133
	v_fmamk_f32 v87, v87, 0x3dd53b94, v133
	v_fmamk_f32 v88, v88, 0x3dd53b94, v133
	v_exp_f32_e32 v80, v80
	v_mfma_f32_32x32x16_bf16 v[48:63], v[200:203], v[218:221], v[48:63]
	ds_read_b64_tr_b16 v[218:219], v246 offset:1536
	ds_read_b64_tr_b16 v[220:221], v246 offset:3584
	v_fmamk_f32 v89, v89, 0x3dd53b94, v133
	v_exp_f32_e32 v81, v81
	v_fmamk_f32 v90, v90, 0x3dd53b94, v133
	v_exp_f32_e32 v82, v82
	s_waitcnt lgkmcnt(6)
	v_mfma_f32_32x32x16_bf16 v[32:47], v[188:191], v[222:225], v[32:47]
	ds_read_b64_tr_b16 v[222:223], v246 offset:5632
	ds_read_b64_tr_b16 v[224:225], v246 offset:7680
	v_fmamk_f32 v91, v91, 0x3dd53b94, v133
	v_exp_f32_e32 v83, v83
	v_fmamk_f32 v92, v92, 0x3dd53b94, v133
	v_exp_f32_e32 v84, v84
	v_mfma_f32_32x32x16_bf16 v[32:47], v[192:195], v[184:187], v[32:47]
	ds_read_b64_tr_b16 v[184:185], v246 offset:9728
	ds_read_b64_tr_b16 v[186:187], v246 offset:11776
	v_fmamk_f32 v93, v93, 0x3dd53b94, v133
	v_exp_f32_e32 v85, v85
	v_fmamk_f32 v94, v94, 0x3dd53b94, v133
	v_exp_f32_e32 v86, v86
	s_waitcnt lgkmcnt(6)
	v_mfma_f32_32x32x16_bf16 v[32:47], v[196:199], v[210:213], v[32:47]
	ds_read_b64_tr_b16 v[210:211], v246 offset:13824
	ds_read_b64_tr_b16 v[212:213], v246 offset:15872
	v_fmamk_f32 v95, v95, 0x3dd53b94, v133
	v_exp_f32_e32 v87, v87
	v_fmamk_f32 v64, v64, 0x3dd53b94, v133
	v_fmamk_f32 v65, v65, 0x3dd53b94, v133
	v_add_u32_e32 v134, s14, v174
	s_waitcnt vmcnt(3)
	ds_write_b128 v134, v[148:151]
	v_mfma_f32_32x32x16_bf16 v[32:47], v[200:203], v[214:217], v[32:47]
	v_exp_f32_e32 v88, v88
	v_fmamk_f32 v66, v66, 0x3dd53b94, v133
	v_fmamk_f32 v67, v67, 0x3dd53b94, v133
	v_exp_f32_e32 v89, v89
	v_add_u32_e32 v135, s14, v175
	s_waitcnt vmcnt(1)
	ds_write_b128 v135, v[156:159]
	s_waitcnt lgkmcnt(6)
	v_mfma_f32_32x32x16_bf16 v[16:31], v[188:191], v[218:221], v[16:31]
	v_fmamk_f32 v68, v68, 0x3dd53b94, v133
	v_fmamk_f32 v69, v69, 0x3dd53b94, v133
	v_exp_f32_e32 v90, v90
	v_fmamk_f32 v70, v70, 0x3dd53b94, v133
	v_fmamk_f32 v71, v71, 0x3dd53b94, v133
	v_add_u32_e32 v134, s15, v179
	ds_write_b128 v134, v[144:147] offset:49152
	ds_write_b128 v134, v[152:155] offset:61440
	v_mfma_f32_32x32x16_bf16 v[16:31], v[192:195], v[222:225], v[16:31]
	v_exp_f32_e32 v91, v91
	v_fmamk_f32 v72, v72, 0x3dd53b94, v133
	v_fmamk_f32 v73, v73, 0x3dd53b94, v133
	v_exp_f32_e32 v92, v92
	v_add_u32_e32 v135, s15, v180
	s_waitcnt vmcnt(0)
	ds_write_b128 v135, v[204:207] offset:49152
	s_waitcnt lgkmcnt(5)
	v_mfma_f32_32x32x16_bf16 v[16:31], v[196:199], v[184:187], v[16:31]
	v_fmamk_f32 v74, v74, 0x3dd53b94, v133
	v_fmamk_f32 v75, v75, 0x3dd53b94, v133
	v_exp_f32_e32 v93, v93
	v_fmamk_f32 v76, v76, 0x3dd53b94, v133
	v_fmamk_f32 v77, v77, 0x3dd53b94, v133
	v_mfma_f32_32x32x16_bf16 v[16:31], v[200:203], v[210:213], v[16:31]
	v_exp_f32_e32 v94, v94
	v_fmamk_f32 v78, v78, 0x3dd53b94, v133
	v_fmamk_f32 v79, v79, 0x3dd53b94, v133
	v_exp_f32_e32 v95, v95
	s_cbranch_vccz .Lattn_skip2
	s_and_saveexec_b64 s[12:13], s[4:5]
	ds_write_b32 v169, v249 offset:128
	s_or_b64 exec, exec, s[12:13]
	s_waitcnt lgkmcnt(0)
	v_add_u32_e32 v250, v168, v208
	ds_read_b128 v[128:131], v250 offset:128
	ds_read_b128 v[132:135], v250 offset:160
	ds_read_b128 v[136:139], v250 offset:192
	ds_read_b128 v[140:143], v250 offset:224
	s_waitcnt lgkmcnt(0)
	v_pk_mul_f32 v[0:1], v[0:1], v[128:129]
	v_pk_mul_f32 v[2:3], v[2:3], v[130:131]
	v_pk_mul_f32 v[4:5], v[4:5], v[132:133]
	v_pk_mul_f32 v[6:7], v[6:7], v[134:135]
	v_pk_mul_f32 v[8:9], v[8:9], v[136:137]
	v_pk_mul_f32 v[10:11], v[10:11], v[138:139]
	v_pk_mul_f32 v[12:13], v[12:13], v[140:141]
	v_pk_mul_f32 v[14:15], v[14:15], v[142:143]
	v_pk_mul_f32 v[48:49], v[48:49], v[128:129]
	v_pk_mul_f32 v[50:51], v[50:51], v[130:131]
	v_pk_mul_f32 v[52:53], v[52:53], v[132:133]
	v_pk_mul_f32 v[54:55], v[54:55], v[134:135]
	v_pk_mul_f32 v[56:57], v[56:57], v[136:137]
	v_pk_mul_f32 v[58:59], v[58:59], v[138:139]
	v_pk_mul_f32 v[60:61], v[60:61], v[140:141]
	v_pk_mul_f32 v[62:63], v[62:63], v[142:143]
	v_pk_mul_f32 v[32:33], v[32:33], v[128:129]
	v_pk_mul_f32 v[34:35], v[34:35], v[130:131]
	v_pk_mul_f32 v[36:37], v[36:37], v[132:133]
	v_pk_mul_f32 v[38:39], v[38:39], v[134:135]
	v_pk_mul_f32 v[40:41], v[40:41], v[136:137]
	v_pk_mul_f32 v[42:43], v[42:43], v[138:139]
	v_pk_mul_f32 v[44:45], v[44:45], v[140:141]
	v_pk_mul_f32 v[46:47], v[46:47], v[142:143]
	v_pk_mul_f32 v[16:17], v[16:17], v[128:129]
	v_pk_mul_f32 v[18:19], v[18:19], v[130:131]
	v_pk_mul_f32 v[20:21], v[20:21], v[132:133]
	v_pk_mul_f32 v[22:23], v[22:23], v[134:135]
	v_pk_mul_f32 v[24:25], v[24:25], v[136:137]
	v_pk_mul_f32 v[26:27], v[26:27], v[138:139]
	v_pk_mul_f32 v[28:29], v[28:29], v[140:141]
	v_pk_mul_f32 v[30:31], v[30:31], v[142:143]
